# speedup vs baseline: 1.0331x; 1.0050x over previous
; DI unsigned pk2(float lo, float hi) { const f32x2 v = {lo, hi}; return __builtin_bit_cast(unsigned, __builtin_convertvector(v, bf16x2_t)); }
; DI void mixer_tile(unsigned char* smem_, const Params& p, int layer, const bf16_t* __restrict__ proj, bf16_t* __restrict__ y, int tile_) {
;     ...
;         const int g = tid >> 6, win = 2 << g;
;         const int l31 = lane & 31, hi = lane >> 5;
;         const float* pw = p.in[6] + ((size_t)(layer * 4 + g) * 64) * 64;
;         bf16x8 wf[2][4];
; #pragma unroll
;         for (int eh = 0; eh < 2; ++eh)
; #pragma unroll
;             for (int kk = 0; kk < 4; ++kk) {
;                 const float* wp = pw + (size_t)(16 * kk + 8 * hi) * 64 + 32 * eh + l31;
;                 u32x4 w; w.x = pk2(wp[0], wp[64]); w.y = pk2(wp[128], wp[192]); w.z = pk2(wp[256], wp[320]); w.w = pk2(wp[384], wp[448]);
;                 wf[eh][kk] = __builtin_bit_cast(bf16x8, w);
;             }
.LBB0_178:
	s_or_b64 exec, exec, s[0:1]
	v_lshrrev_b32_sdwa v73, v208, v68 dst_sel:DWORD dst_unused:UNUSED_PAD src0_sel:DWORD src1_sel:BYTE_0
	v_or_b32_e32 v0, s16, v73
	v_ashrrev_i32_e32 v1, 31, v0
	v_readlane_b32 s36, v252, 2
	v_lshlrev_b64 v[0:1], 14, v[0:1]
	v_readlane_b32 s48, v252, 14
	v_readlane_b32 s49, v252, 15
	v_lshrrev_b32_e32 v69, 5, v26
	v_lshlrev_b32_e32 v2, 2, v67
	v_lshl_add_u64 v[0:1], s[48:49], 0, v[0:1]
	v_mov_b32_e32 v3, v129
	v_lshl_add_u64 v[4:5], v[0:1], 0, v[2:3]
	v_lshlrev_b32_e32 v6, 11, v69
	v_mov_b32_e32 v7, v129
	v_lshl_add_u64 v[12:13], v[4:5], 0, v[6:7]
	s_waitcnt lgkmcnt(0)
	s_barrier
	global_load_dword v0, v[12:13], off
	global_load_dword v18, v[12:13], off offset:256
	v_or_b32_e32 v14, 0x1000, v6
	v_mov_b32_e32 v15, v129
	v_lshl_add_u64 v[8:9], v[4:5], 0, v[14:15]
	v_mov_b32_e32 v11, v129
	v_cmp_lt_u32_sdwa s[0:1], v68, v209 src0_sel:BYTE_0 src1_sel:DWORD
	s_movk_i32 s2, 0x7f
	v_cmp_gt_u32_sdwa vcc, v68, s2 src0_sel:BYTE_0 src1_sel:DWORD
	v_cmp_eq_u32_e64 s[2:3], 3, v73
	v_lshlrev_b32_e64 v71, v73, 2
	s_or_b32 s20, s18, 1
	v_readlane_b32 s37, v252, 3
	v_readlane_b32 s38, v252, 4
	v_readlane_b32 s39, v252, 5
	v_readlane_b32 s40, v252, 6
	v_readlane_b32 s41, v252, 7
	v_readlane_b32 s42, v252, 8
	v_readlane_b32 s43, v252, 9
	v_readlane_b32 s44, v252, 10
	v_readlane_b32 s45, v252, 11
	v_readlane_b32 s46, v252, 12
	v_readlane_b32 s47, v252, 13
	v_readlane_b32 s50, v252, 16
	v_readlane_b32 s51, v252, 17
	global_load_dword v1, v[12:13], off offset:512
	global_load_dword v19, v[12:13], off offset:768
	global_load_dword v2, v[12:13], off offset:1024
	global_load_dword v20, v[12:13], off offset:1280
	global_load_dword v3, v[12:13], off offset:1536
	global_load_dword v21, v[12:13], off offset:1792
	global_load_dword v32, v[8:9], off
	global_load_dword v22, v[8:9], off offset:256
	global_load_dword v33, v[8:9], off offset:512
	global_load_dword v23, v[8:9], off offset:768
	global_load_dword v34, v[8:9], off offset:1024
	global_load_dword v24, v[8:9], off offset:1280
	global_load_dword v35, v[8:9], off offset:1536
	s_nop 0
	global_load_dword v25, v[8:9], off offset:1792
	v_or_b32_e32 v10, 0x2000, v6
	v_lshl_add_u64 v[8:9], v[4:5], 0, v[10:11]
	global_load_dword v36, v[8:9], off
	global_load_dword v26, v[8:9], off offset:256
	global_load_dword v37, v[8:9], off offset:512
	global_load_dword v27, v[8:9], off offset:768
	global_load_dword v38, v[8:9], off offset:1024
	global_load_dword v28, v[8:9], off offset:1280
	global_load_dword v39, v[8:9], off offset:1536
	s_nop 0
	global_load_dword v29, v[8:9], off offset:1792
	v_mov_b32_e32 v9, v129
	v_or_b32_e32 v8, 0x3000, v6
	v_lshl_add_u64 v[6:7], v[4:5], 0, v[8:9]
	global_load_dword v40, v[6:7], off
	global_load_dword v30, v[6:7], off offset:256
	global_load_dword v41, v[6:7], off offset:512
	global_load_dword v31, v[6:7], off offset:768
	global_load_dword v42, v[6:7], off offset:1024
	global_load_dword v56, v[6:7], off offset:1280
	global_load_dword v43, v[6:7], off offset:1536
	s_nop 0
	global_load_dword v57, v[6:7], off offset:1792
	s_waitcnt vmcnt(0)
	v_cvt_pk_bf16_f32 v0, v0, v18
	v_cvt_pk_bf16_f32 v1, v1, v19
	v_cvt_pk_bf16_f32 v2, v2, v20
	v_cvt_pk_bf16_f32 v3, v3, v21
	v_cvt_pk_bf16_f32 v32, v32, v22
	v_cvt_pk_bf16_f32 v33, v33, v23
	v_cvt_pk_bf16_f32 v34, v34, v24
	v_cvt_pk_bf16_f32 v35, v35, v25
	v_cvt_pk_bf16_f32 v36, v36, v26
	v_cvt_pk_bf16_f32 v37, v37, v27
	v_cvt_pk_bf16_f32 v38, v38, v28
	v_cvt_pk_bf16_f32 v39, v39, v29
	v_cvt_pk_bf16_f32 v40, v40, v30
	v_cvt_pk_bf16_f32 v41, v41, v31
	v_cvt_pk_bf16_f32 v42, v42, v56
	v_cvt_pk_bf16_f32 v43, v43, v57
	v_lshl_add_u64 v[16:17], v[4:5], 0, s[66:67]
	global_load_dword v58, v[12:13], off offset:128
	global_load_dword v18, v[12:13], off offset:384
	v_lshl_add_u64 v[10:11], v[16:17], 0, v[10:11]
	v_lshl_add_u64 v[8:9], v[16:17], 0, v[8:9]
	global_load_dword v59, v[12:13], off offset:640
	global_load_dword v19, v[12:13], off offset:896
	global_load_dword v60, v[12:13], off offset:1152
	global_load_dword v20, v[12:13], off offset:1408
	global_load_dword v61, v[12:13], off offset:1664
	s_nop 0
	global_load_dword v21, v[12:13], off offset:1920
	v_lshl_add_u64 v[12:13], v[16:17], 0, v[14:15]
	global_load_dword v44, v[12:13], off
	global_load_dword v22, v[12:13], off offset:256
	global_load_dword v45, v[12:13], off offset:512
	global_load_dword v23, v[12:13], off offset:768
	global_load_dword v46, v[12:13], off offset:1024
	global_load_dword v24, v[12:13], off offset:1280
	global_load_dword v47, v[12:13], off offset:1536
	s_nop 0
	global_load_dword v25, v[12:13], off offset:1792
	global_load_dword v48, v[10:11], off
	global_load_dword v26, v[10:11], off offset:256
	global_load_dword v49, v[10:11], off offset:512
	global_load_dword v27, v[10:11], off offset:768
	global_load_dword v50, v[10:11], off offset:1024
	global_load_dword v28, v[10:11], off offset:1280
	global_load_dword v51, v[10:11], off offset:1536
	s_nop 0
	global_load_dword v29, v[10:11], off offset:1792
	global_load_dword v52, v[8:9], off
	global_load_dword v30, v[8:9], off offset:256
	global_load_dword v53, v[8:9], off offset:512
	global_load_dword v31, v[8:9], off offset:768
	global_load_dword v54, v[8:9], off offset:1024
	global_load_dword v56, v[8:9], off offset:1280
	global_load_dword v55, v[8:9], off offset:1536
	s_nop 0
	global_load_dword v57, v[8:9], off offset:1792
	s_waitcnt vmcnt(0)
; DI unsigned pk2(float lo, float hi) { const f32x2 v = {lo, hi}; return __builtin_bit_cast(unsigned, __builtin_convertvector(v, bf16x2_t)); }
; DI void mixer_tile(unsigned char* smem_, const Params& p, int layer, const bf16_t* __restrict__ proj, bf16_t* __restrict__ y, int tile_) {
;     ...
;                 u32x4 w; w.x = pk2(wp[0], wp[64]); w.y = pk2(wp[128], wp[192]); w.z = pk2(wp[256], wp[320]); w.w = pk2(wp[384], wp[448]);
;                 wf[eh][kk] = __builtin_bit_cast(bf16x8, w);
;             }
;         float pv[47];
; #pragma unroll
;         for (int r = 0; r < 47; ++r) pv[r] = U[r * 256 + tid];
; #pragma unroll
;         for (int t = 0; t < 32; ++t) {
;             float s = 0.f;
; #pragma unroll
;             for (int j = 0; j < 16; ++j) s += (j < win) ? pv[t + 15 - j] : 0.f;
;             const int cnt = min(pos0 + t + 1, win);
;             U[t * 256 + tid] = s * __builtin_amdgcn_rcpf((float)cnt) - pv[t + 15];
;         }
	v_cvt_pk_bf16_f32 v4, v58, v18
	v_cvt_pk_bf16_f32 v5, v59, v19
	v_cvt_pk_bf16_f32 v6, v60, v20
	v_cvt_pk_bf16_f32 v7, v61, v21
	v_cvt_pk_bf16_f32 v44, v44, v22
	v_cvt_pk_bf16_f32 v45, v45, v23
	v_cvt_pk_bf16_f32 v46, v46, v24
	v_cvt_pk_bf16_f32 v47, v47, v25
	v_cvt_pk_bf16_f32 v48, v48, v26
	v_cvt_pk_bf16_f32 v49, v49, v27
	v_cvt_pk_bf16_f32 v50, v50, v28
	v_cvt_pk_bf16_f32 v51, v51, v29
	v_cvt_pk_bf16_f32 v52, v52, v30
	v_cvt_pk_bf16_f32 v53, v53, v31
	v_cvt_pk_bf16_f32 v54, v54, v56
	v_cvt_pk_bf16_f32 v55, v55, v57
	ds_read2st64_b32 v[74:75], v72 offset1:4
	ds_read2st64_b32 v[76:77], v72 offset0:8 offset1:12
	ds_read2st64_b32 v[78:79], v72 offset0:16 offset1:20
	ds_read2st64_b32 v[80:81], v72 offset0:24 offset1:28
	ds_read2st64_b32 v[82:83], v72 offset0:32 offset1:36
	ds_read2st64_b32 v[84:85], v72 offset0:40 offset1:44
	ds_read2st64_b32 v[64:65], v72 offset0:48 offset1:52
	ds_read2st64_b32 v[62:63], v72 offset0:56 offset1:60
	ds_read2st64_b32 v[60:61], v72 offset0:64 offset1:68
	ds_read2st64_b32 v[58:59], v72 offset0:72 offset1:76
	ds_read2st64_b32 v[56:57], v72 offset0:80 offset1:84
	ds_read2st64_b32 v[30:31], v72 offset0:88 offset1:92
	ds_read2st64_b32 v[28:29], v72 offset0:96 offset1:100
	ds_read2st64_b32 v[26:27], v72 offset0:104 offset1:108
	ds_read2st64_b32 v[24:25], v72 offset0:112 offset1:116
	ds_read2st64_b32 v[22:23], v72 offset0:120 offset1:124
	ds_read2st64_b32 v[20:21], v72 offset0:128 offset1:132
	ds_read2st64_b32 v[18:19], v72 offset0:136 offset1:140
	ds_read2st64_b32 v[14:15], v72 offset0:144 offset1:148
	ds_read2st64_b32 v[8:9], v72 offset0:152 offset1:156
	ds_read2st64_b32 v[16:17], v72 offset0:160 offset1:164
	ds_read2st64_b32 v[10:11], v72 offset0:168 offset1:172
	ds_read2st64_b32 v[12:13], v72 offset0:176 offset1:180
	ds_read_b32 v70, v72 offset:47104
	s_waitcnt lgkmcnt(14)
	v_add_f32_e32 v86, 0, v63
	v_add_f32_e32 v86, v62, v86
	v_cndmask_b32_e64 v87, v65, 0, s[0:1]
	v_add_f32_e32 v86, v87, v86
	v_cndmask_b32_e64 v90, v64, 0, s[0:1]
	v_add_f32_e32 v86, v90, v86
	v_cndmask_b32_e32 v90, 0, v85, vcc
	v_add_f32_e32 v86, v90, v86
	v_cndmask_b32_e32 v91, 0, v84, vcc
	v_add_f32_e32 v86, v91, v86
	v_cndmask_b32_e32 v93, 0, v83, vcc
	v_add_f32_e32 v86, v93, v86
	v_cndmask_b32_e32 v94, 0, v82, vcc
	v_add_f32_e32 v86, v94, v86
	v_cndmask_b32_e64 v73, 0, v81, s[2:3]
	v_add_f32_e32 v81, v73, v86
	v_cndmask_b32_e64 v80, 0, v80, s[2:3]
	v_add_f32_e32 v81, v80, v81
	v_cndmask_b32_e64 v79, 0, v79, s[2:3]
	v_add_f32_e32 v81, v79, v81
	v_cndmask_b32_e64 v78, 0, v78, s[2:3]
	v_add_f32_e32 v81, v78, v81
	v_cndmask_b32_e64 v77, 0, v77, s[2:3]
	v_add_f32_e32 v81, v77, v81
	v_cndmask_b32_e64 v76, 0, v76, s[2:3]
	v_add_f32_e32 v81, v76, v81
	v_cndmask_b32_e64 v75, 0, v75, s[2:3]
	v_add_f32_e32 v81, v75, v81
	v_cndmask_b32_e64 v74, 0, v74, s[2:3]
	v_add_f32_e32 v74, v74, v81
	v_min_u32_e32 v81, s20, v71
	v_cvt_f32_ubyte0_e32 v81, v81
	v_rcp_iflag_f32_e32 v81, v81
	v_cndmask_b32_e64 v86, v62, 0, s[0:1]
	v_cndmask_b32_e64 v82, 0, v82, s[2:3]
	s_or_b32 s20, s18, 2
	v_fma_f32 v74, v81, v74, -v63
	v_add_f32_e32 v81, 0, v60
	v_add_f32_e32 v81, v63, v81
	v_add_f32_e32 v81, v86, v81
	v_add_f32_e32 v81, v87, v81
	v_cndmask_b32_e32 v87, 0, v64, vcc
	v_add_f32_e32 v81, v87, v81
	v_add_f32_e32 v81, v90, v81
	v_add_f32_e32 v81, v91, v81
	v_add_f32_e32 v81, v93, v81
	v_add_f32_e32 v81, v82, v81
	v_add_f32_e32 v81, v73, v81
	v_add_f32_e32 v81, v80, v81
	v_add_f32_e32 v81, v79, v81
	v_add_f32_e32 v81, v78, v81
	v_add_f32_e32 v81, v77, v81
	v_add_f32_e32 v81, v76, v81
	v_add_f32_e32 v75, v75, v81
	v_min_u32_e32 v81, s20, v71
	v_cvt_f32_ubyte0_e32 v81, v81
	v_rcp_iflag_f32_e32 v81, v81
	v_cndmask_b32_e64 v83, 0, v83, s[2:3]
	s_or_b32 s20, s18, 3
	v_cndmask_b32_e64 v84, 0, v84, s[2:3]
	v_fma_f32 v75, v81, v75, -v60
	ds_write2st64_b32 v72, v74, v75 offset1:4
	v_add_f32_e32 v74, 0, v61
	v_add_f32_e32 v74, v60, v74
	v_cndmask_b32_e64 v75, v63, 0, s[0:1]
	v_add_f32_e32 v74, v75, v74
	v_add_f32_e32 v74, v86, v74
	v_cndmask_b32_e32 v81, 0, v65, vcc
	v_add_f32_e32 v74, v81, v74
	v_add_f32_e32 v74, v87, v74
	v_add_f32_e32 v74, v90, v74
	v_add_f32_e32 v74, v91, v74
	v_add_f32_e32 v74, v83, v74
	v_add_f32_e32 v74, v82, v74
	v_add_f32_e32 v74, v73, v74
	v_add_f32_e32 v74, v80, v74
	v_add_f32_e32 v74, v79, v74
	v_add_f32_e32 v74, v78, v74
	v_add_f32_e32 v74, v77, v74
	v_add_f32_e32 v74, v76, v74
	v_min_u32_e32 v76, s20, v71
	v_cvt_f32_ubyte0_e32 v76, v76
	v_rcp_iflag_f32_e32 v76, v76
	v_cndmask_b32_e64 v86, v60, 0, s[0:1]
	s_or_b32 s20, s18, 4
	v_cndmask_b32_e64 v85, 0, v85, s[2:3]
	v_fma_f32 v74, v76, v74, -v61
	v_add_f32_e32 v76, 0, v58
	v_add_f32_e32 v76, v61, v76
	v_add_f32_e32 v76, v86, v76
	v_add_f32_e32 v75, v75, v76
	v_cndmask_b32_e32 v76, 0, v62, vcc
	v_add_f32_e32 v75, v76, v75
	v_add_f32_e32 v75, v81, v75
	v_add_f32_e32 v75, v87, v75
	v_add_f32_e32 v75, v90, v75
	v_add_f32_e32 v75, v84, v75
	v_add_f32_e32 v75, v83, v75
	v_add_f32_e32 v75, v82, v75
	v_add_f32_e32 v75, v73, v75
	v_add_f32_e32 v75, v80, v75
	v_add_f32_e32 v75, v79, v75
	v_add_f32_e32 v75, v78, v75
	v_add_f32_e32 v75, v77, v75
	v_min_u32_e32 v77, s20, v71
	v_cvt_f32_ubyte0_e32 v77, v77
	v_rcp_iflag_f32_e32 v77, v77
	s_or_b32 s20, s18, 5
	v_cndmask_b32_e64 v64, 0, v64, s[2:3]
	v_cndmask_b32_e64 v65, 0, v65, s[2:3]
	v_fma_f32 v75, v77, v75, -v58
	ds_write2st64_b32 v72, v74, v75 offset0:8 offset1:12
	v_add_f32_e32 v74, 0, v59
	v_add_f32_e32 v74, v58, v74
	v_cndmask_b32_e64 v75, v61, 0, s[0:1]
	v_add_f32_e32 v74, v75, v74
	v_add_f32_e32 v74, v86, v74
	v_cndmask_b32_e32 v77, 0, v63, vcc
	v_add_f32_e32 v74, v77, v74
	v_add_f32_e32 v74, v76, v74
	v_add_f32_e32 v74, v81, v74
	v_add_f32_e32 v74, v87, v74
	v_add_f32_e32 v74, v85, v74
	v_add_f32_e32 v74, v84, v74
	v_add_f32_e32 v74, v83, v74
	v_add_f32_e32 v74, v82, v74
	v_add_f32_e32 v74, v73, v74
	v_add_f32_e32 v74, v80, v74
	v_add_f32_e32 v74, v79, v74
	v_add_f32_e32 v74, v78, v74
	v_min_u32_e32 v78, s20, v71
	v_cvt_f32_ubyte0_e32 v78, v78
	v_rcp_iflag_f32_e32 v78, v78
	v_cndmask_b32_e64 v86, v58, 0, s[0:1]
	s_or_b32 s20, s18, 6
	v_cndmask_b32_e64 v62, 0, v62, s[2:3]
	v_fma_f32 v74, v78, v74, -v59
	s_waitcnt lgkmcnt(14)
; DI void mixer_tile(unsigned char* smem_, const Params& p, int layer, const bf16_t* __restrict__ proj, bf16_t* __restrict__ y, int tile_) {
;     ...
;         float pv[47];
; #pragma unroll
;         for (int r = 0; r < 47; ++r) pv[r] = U[r * 256 + tid];
; #pragma unroll
;         for (int t = 0; t < 32; ++t) {
;             float s = 0.f;
; #pragma unroll
;             for (int j = 0; j < 16; ++j) s += (j < win) ? pv[t + 15 - j] : 0.f;
;             const int cnt = min(pos0 + t + 1, win);
;             U[t * 256 + tid] = s * __builtin_amdgcn_rcpf((float)cnt) - pv[t + 15];
;         }
	v_add_f32_e32 v78, 0, v56
	v_add_f32_e32 v78, v59, v78
	v_add_f32_e32 v78, v86, v78
	v_add_f32_e32 v75, v75, v78
	v_cndmask_b32_e32 v78, 0, v60, vcc
	v_add_f32_e32 v75, v78, v75
	v_add_f32_e32 v75, v77, v75
	v_add_f32_e32 v75, v76, v75
	v_add_f32_e32 v75, v81, v75
	v_add_f32_e32 v75, v64, v75
	v_add_f32_e32 v75, v85, v75
	v_add_f32_e32 v75, v84, v75
	v_add_f32_e32 v75, v83, v75
	v_add_f32_e32 v75, v82, v75
	v_add_f32_e32 v75, v73, v75
	v_add_f32_e32 v75, v80, v75
	v_add_f32_e32 v75, v79, v75
	v_min_u32_e32 v79, s20, v71
	v_cvt_f32_ubyte0_e32 v79, v79
	v_rcp_iflag_f32_e32 v79, v79
	s_or_b32 s20, s18, 7
	v_cndmask_b32_e64 v63, 0, v63, s[2:3]
	v_cndmask_b32_e64 v60, 0, v60, s[2:3]
	v_fma_f32 v75, v79, v75, -v56
	ds_write2st64_b32 v72, v74, v75 offset0:16 offset1:20
	v_add_f32_e32 v74, 0, v57
	v_add_f32_e32 v74, v56, v74
	v_cndmask_b32_e64 v75, v59, 0, s[0:1]
	v_add_f32_e32 v74, v75, v74
	v_add_f32_e32 v74, v86, v74
	v_cndmask_b32_e32 v79, 0, v61, vcc
	v_add_f32_e32 v74, v79, v74
	v_add_f32_e32 v74, v78, v74
	v_add_f32_e32 v74, v77, v74
	v_add_f32_e32 v74, v76, v74
	v_add_f32_e32 v74, v65, v74
	v_add_f32_e32 v74, v64, v74
	v_add_f32_e32 v74, v85, v74
	v_min_u32_e32 v76, s20, v71
	v_add_f32_e32 v74, v84, v74
	v_cvt_f32_ubyte0_e32 v76, v76
	v_add_f32_e32 v74, v83, v74
	v_rcp_iflag_f32_e32 v76, v76
	v_add_f32_e32 v74, v82, v74
	v_add_f32_e32 v74, v73, v74
	v_add_f32_e32 v74, v80, v74
	v_fma_f32 v74, v76, v74, -v57
	v_add_f32_e32 v76, 0, v30
	v_add_f32_e32 v76, v57, v76
	v_cndmask_b32_e64 v80, v56, 0, s[0:1]
	v_add_f32_e32 v76, v80, v76
	v_add_f32_e32 v75, v75, v76
	v_cndmask_b32_e32 v76, 0, v58, vcc
	v_add_f32_e32 v75, v76, v75
	v_add_f32_e32 v75, v79, v75
	v_add_f32_e32 v75, v78, v75
	v_add_f32_e32 v75, v77, v75
	v_add_f32_e32 v75, v62, v75
	v_add_f32_e32 v75, v65, v75
	v_add_f32_e32 v75, v64, v75
	v_add_f32_e32 v75, v85, v75
	v_add_f32_e32 v75, v84, v75
	v_add_f32_e32 v75, v83, v75
	v_add_f32_e32 v75, v82, v75
	s_or_b32 s20, s18, 8
	v_add_f32_e32 v73, v73, v75
	v_min_u32_e32 v75, s20, v71
	v_cvt_f32_ubyte0_e32 v75, v75
	v_rcp_iflag_f32_e32 v75, v75
	s_or_b32 s20, s18, 9
	v_min_u32_e32 v77, s20, v71
	v_cvt_f32_ubyte0_e32 v77, v77
	v_fma_f32 v73, v75, v73, -v30
	ds_write2st64_b32 v72, v74, v73 offset0:24 offset1:28
	v_add_f32_e32 v73, 0, v31
	v_add_f32_e32 v73, v30, v73
	v_cndmask_b32_e64 v74, v57, 0, s[0:1]
	v_add_f32_e32 v73, v74, v73
	v_add_f32_e32 v73, v80, v73
	v_cndmask_b32_e32 v75, 0, v59, vcc
	v_add_f32_e32 v73, v75, v73
	v_add_f32_e32 v73, v76, v73
	v_add_f32_e32 v73, v79, v73
	v_add_f32_e32 v73, v78, v73
	v_add_f32_e32 v73, v63, v73
	v_add_f32_e32 v73, v62, v73
	v_add_f32_e32 v73, v65, v73
	v_add_f32_e32 v73, v64, v73
	v_add_f32_e32 v73, v85, v73
	v_rcp_iflag_f32_e32 v77, v77
	v_add_f32_e32 v73, v84, v73
	v_add_f32_e32 v73, v83, v73
	v_add_f32_e32 v73, v82, v73
	v_fma_f32 v73, v77, v73, -v31
	s_waitcnt lgkmcnt(14)
	v_add_f32_e32 v77, 0, v28
	v_add_f32_e32 v77, v31, v77
	v_cndmask_b32_e64 v78, v30, 0, s[0:1]
	v_add_f32_e32 v77, v78, v77
	v_add_f32_e32 v74, v74, v77
	v_cndmask_b32_e32 v77, 0, v56, vcc
	v_add_f32_e32 v74, v77, v74
	v_add_f32_e32 v74, v75, v74
	v_add_f32_e32 v74, v76, v74
	v_add_f32_e32 v74, v79, v74
	v_add_f32_e32 v74, v60, v74
	v_add_f32_e32 v74, v63, v74
	s_or_b32 s20, s18, 10
	v_add_f32_e32 v74, v62, v74
	v_min_u32_e32 v79, s20, v71
	v_add_f32_e32 v74, v65, v74
	v_cvt_f32_ubyte0_e32 v79, v79
	v_add_f32_e32 v74, v64, v74
	v_rcp_iflag_f32_e32 v79, v79
	v_add_f32_e32 v74, v85, v74
	v_add_f32_e32 v74, v84, v74
	v_add_f32_e32 v74, v83, v74
	v_fma_f32 v74, v79, v74, -v28
	ds_write2st64_b32 v72, v73, v74 offset0:32 offset1:36
	v_add_f32_e32 v73, 0, v29
	v_add_f32_e32 v73, v28, v73
	v_cndmask_b32_e64 v74, v31, 0, s[0:1]
	v_add_f32_e32 v73, v74, v73
	v_add_f32_e32 v73, v78, v73
	v_cndmask_b32_e32 v78, 0, v57, vcc
	v_add_f32_e32 v73, v78, v73
	v_add_f32_e32 v73, v77, v73
	v_add_f32_e32 v73, v75, v73
	v_add_f32_e32 v73, v76, v73
	v_cndmask_b32_e64 v61, 0, v61, s[2:3]
	v_add_f32_e32 v73, v61, v73
	v_add_f32_e32 v73, v60, v73
	s_or_b32 s20, s18, 11
	v_add_f32_e32 v73, v63, v73
	v_min_u32_e32 v76, s20, v71
	v_add_f32_e32 v73, v62, v73
	v_cvt_f32_ubyte0_e32 v76, v76
	v_add_f32_e32 v73, v65, v73
	v_rcp_iflag_f32_e32 v76, v76
	v_add_f32_e32 v73, v64, v73
	v_add_f32_e32 v73, v85, v73
	v_add_f32_e32 v73, v84, v73
	v_fma_f32 v73, v76, v73, -v29
	v_add_f32_e32 v76, 0, v26
	v_add_f32_e32 v76, v29, v76
	v_cndmask_b32_e64 v79, v28, 0, s[0:1]
	v_add_f32_e32 v76, v79, v76
	v_add_f32_e32 v74, v74, v76
	v_cndmask_b32_e32 v76, 0, v30, vcc
	v_add_f32_e32 v74, v76, v74
	v_add_f32_e32 v74, v78, v74
	v_add_f32_e32 v74, v77, v74
	v_add_f32_e32 v74, v75, v74
	v_cndmask_b32_e64 v58, 0, v58, s[2:3]
	v_add_f32_e32 v74, v58, v74
	v_add_f32_e32 v74, v61, v74
	s_or_b32 s20, s18, 12
	v_add_f32_e32 v74, v60, v74
	v_min_u32_e32 v75, s20, v71
	v_add_f32_e32 v74, v63, v74
	v_cvt_f32_ubyte0_e32 v75, v75
	v_add_f32_e32 v74, v62, v74
	v_rcp_iflag_f32_e32 v75, v75
	v_add_f32_e32 v74, v65, v74
	v_add_f32_e32 v74, v64, v74
	v_add_f32_e32 v74, v85, v74
	v_fma_f32 v74, v75, v74, -v26
	ds_write2st64_b32 v72, v73, v74 offset0:40 offset1:44
	v_add_f32_e32 v73, 0, v27
	v_add_f32_e32 v73, v26, v73
	v_cndmask_b32_e64 v74, v29, 0, s[0:1]
	v_add_f32_e32 v73, v74, v73
	v_add_f32_e32 v73, v79, v73
	v_cndmask_b32_e32 v75, 0, v31, vcc
	v_add_f32_e32 v73, v75, v73
	v_add_f32_e32 v73, v76, v73
	v_add_f32_e32 v73, v78, v73
	v_add_f32_e32 v73, v77, v73
	v_cndmask_b32_e64 v59, 0, v59, s[2:3]
	v_add_f32_e32 v73, v59, v73
	v_add_f32_e32 v73, v58, v73
	v_add_f32_e32 v73, v61, v73
	v_add_f32_e32 v73, v60, v73
	v_add_f32_e32 v73, v63, v73
	v_add_f32_e32 v73, v62, v73
	v_add_f32_e32 v73, v65, v73
	s_or_b32 s20, s18, 13
	v_add_f32_e32 v64, v64, v73
	v_min_u32_e32 v73, s20, v71
	v_cvt_f32_ubyte0_e32 v73, v73
	v_rcp_iflag_f32_e32 v73, v73
	v_cndmask_b32_e64 v77, v26, 0, s[0:1]
	v_cndmask_b32_e64 v56, 0, v56, s[2:3]
	s_or_b32 s20, s18, 14
	v_fma_f32 v64, v73, v64, -v27
	s_waitcnt lgkmcnt(14)
; DI void mixer_tile(unsigned char* smem_, const Params& p, int layer, const bf16_t* __restrict__ proj, bf16_t* __restrict__ y, int tile_) {
;     ...
;         float pv[47];
; #pragma unroll
;         for (int r = 0; r < 47; ++r) pv[r] = U[r * 256 + tid];
; #pragma unroll
;         for (int t = 0; t < 32; ++t) {
;             float s = 0.f;
; #pragma unroll
;             for (int j = 0; j < 16; ++j) s += (j < win) ? pv[t + 15 - j] : 0.f;
;             const int cnt = min(pos0 + t + 1, win);
;             U[t * 256 + tid] = s * __builtin_amdgcn_rcpf((float)cnt) - pv[t + 15];
;         }
	v_add_f32_e32 v73, 0, v24
	v_add_f32_e32 v73, v27, v73
	v_add_f32_e32 v73, v77, v73
	v_add_f32_e32 v73, v74, v73
	v_cndmask_b32_e32 v74, 0, v28, vcc
	v_add_f32_e32 v73, v74, v73
	v_add_f32_e32 v73, v75, v73
	v_add_f32_e32 v73, v76, v73
	v_add_f32_e32 v73, v78, v73
	v_add_f32_e32 v73, v56, v73
	v_add_f32_e32 v73, v59, v73
	v_add_f32_e32 v73, v58, v73
	v_add_f32_e32 v73, v61, v73
	v_add_f32_e32 v73, v60, v73
	v_add_f32_e32 v73, v63, v73
	v_add_f32_e32 v73, v62, v73
	v_add_f32_e32 v65, v65, v73
	v_min_u32_e32 v73, s20, v71
	v_cvt_f32_ubyte0_e32 v73, v73
	v_rcp_iflag_f32_e32 v73, v73
	v_cndmask_b32_e64 v57, 0, v57, s[2:3]
	s_or_b32 s20, s18, 15
	v_cndmask_b32_e64 v30, 0, v30, s[2:3]
	v_fma_f32 v65, v73, v65, -v24
	ds_write2st64_b32 v72, v64, v65 offset0:48 offset1:52
	v_add_f32_e32 v64, 0, v25
	v_add_f32_e32 v64, v24, v64
	v_cndmask_b32_e64 v65, v27, 0, s[0:1]
	v_add_f32_e32 v64, v65, v64
	v_add_f32_e32 v64, v77, v64
	v_cndmask_b32_e32 v73, 0, v29, vcc
	v_add_f32_e32 v64, v73, v64
	v_add_f32_e32 v64, v74, v64
	v_add_f32_e32 v64, v75, v64
	v_add_f32_e32 v64, v76, v64
	v_add_f32_e32 v64, v57, v64
	v_add_f32_e32 v64, v56, v64
	v_add_f32_e32 v64, v59, v64
	v_add_f32_e32 v64, v58, v64
	v_add_f32_e32 v64, v61, v64
	v_add_f32_e32 v64, v60, v64
	v_add_f32_e32 v64, v63, v64
	v_add_f32_e32 v62, v62, v64
	v_min_u32_e32 v64, s20, v71
	v_cvt_f32_ubyte0_e32 v64, v64
	v_rcp_iflag_f32_e32 v64, v64
	v_cndmask_b32_e64 v76, v24, 0, s[0:1]
	v_cndmask_b32_e64 v31, 0, v31, s[2:3]
	v_cndmask_b32_e64 v28, 0, v28, s[2:3]
	v_fma_f32 v62, v64, v62, -v25
	v_add_f32_e32 v64, 0, v22
	v_add_f32_e32 v64, v25, v64
	v_add_f32_e32 v64, v76, v64
	v_add_f32_e32 v64, v65, v64
	v_cndmask_b32_e32 v65, 0, v26, vcc
	v_add_f32_e32 v64, v65, v64
	v_add_f32_e32 v64, v73, v64
	v_add_f32_e32 v64, v74, v64
	v_add_f32_e32 v64, v75, v64
	v_add_f32_e32 v64, v30, v64
	v_add_f32_e32 v64, v57, v64
	v_add_f32_e32 v64, v56, v64
	v_add_f32_e32 v64, v59, v64
	v_add_f32_e32 v64, v58, v64
	v_add_f32_e32 v64, v61, v64
	v_add_f32_e32 v64, v60, v64
	v_add_f32_e32 v63, v63, v64
	v_cvt_f32_ubyte0_e32 v64, v71
	v_rcp_iflag_f32_e32 v64, v64
	v_cndmask_b32_e32 v71, 0, v27, vcc
	v_cndmask_b32_e64 v29, 0, v29, s[2:3]
	v_cndmask_b32_e64 v26, 0, v26, s[2:3]
	v_fma_f32 v63, v64, v63, -v22
	ds_write2st64_b32 v72, v62, v63 offset0:56 offset1:60
	v_add_f32_e32 v62, 0, v23
	v_add_f32_e32 v62, v22, v62
	v_cndmask_b32_e64 v63, v25, 0, s[0:1]
	v_add_f32_e32 v62, v63, v62
	v_add_f32_e32 v62, v76, v62
	v_add_f32_e32 v62, v71, v62
	v_add_f32_e32 v62, v65, v62
	v_add_f32_e32 v62, v73, v62
	v_add_f32_e32 v62, v74, v62
	v_add_f32_e32 v62, v31, v62
	v_add_f32_e32 v62, v30, v62
	v_add_f32_e32 v62, v57, v62
	v_add_f32_e32 v62, v56, v62
	v_add_f32_e32 v62, v59, v62
	v_add_f32_e32 v62, v58, v62
	v_add_f32_e32 v62, v61, v62
	v_add_f32_e32 v60, v60, v62
	s_waitcnt lgkmcnt(14)
	v_add_f32_e32 v62, 0, v20
	v_add_f32_e32 v62, v23, v62
	v_cndmask_b32_e64 v74, v22, 0, s[0:1]
	v_add_f32_e32 v62, v74, v62
	v_add_f32_e32 v62, v63, v62
	v_cndmask_b32_e32 v63, 0, v24, vcc
	v_add_f32_e32 v62, v63, v62
	v_add_f32_e32 v62, v71, v62
	v_add_f32_e32 v62, v65, v62
	v_add_f32_e32 v62, v73, v62
	v_add_f32_e32 v62, v28, v62
	v_add_f32_e32 v62, v31, v62
	v_add_f32_e32 v62, v30, v62
	v_add_f32_e32 v62, v57, v62
	v_add_f32_e32 v62, v56, v62
	v_add_f32_e32 v62, v59, v62
	v_add_f32_e32 v62, v58, v62
	v_add_f32_e32 v61, v61, v62
	v_fma_f32 v60, v64, v60, -v23
	v_fma_f32 v61, v64, v61, -v20
	ds_write2st64_b32 v72, v60, v61 offset0:64 offset1:68
	v_add_f32_e32 v60, 0, v21
	v_add_f32_e32 v60, v20, v60
	v_cndmask_b32_e64 v61, v23, 0, s[0:1]
	v_add_f32_e32 v60, v61, v60
	v_add_f32_e32 v60, v74, v60
	v_cndmask_b32_e32 v62, 0, v25, vcc
	v_add_f32_e32 v60, v62, v60
	v_add_f32_e32 v60, v63, v60
	v_add_f32_e32 v60, v71, v60
	v_add_f32_e32 v60, v65, v60
	v_add_f32_e32 v60, v29, v60
	v_add_f32_e32 v60, v28, v60
	v_add_f32_e32 v60, v31, v60
	v_add_f32_e32 v60, v30, v60
	v_add_f32_e32 v60, v57, v60
	v_add_f32_e32 v60, v56, v60
	v_add_f32_e32 v60, v59, v60
	v_add_f32_e32 v58, v58, v60
	v_add_f32_e32 v60, 0, v18
	v_add_f32_e32 v60, v21, v60
	v_cndmask_b32_e64 v65, v20, 0, s[0:1]
	v_add_f32_e32 v60, v65, v60
	v_add_f32_e32 v60, v61, v60
	v_cndmask_b32_e32 v61, 0, v22, vcc
	v_add_f32_e32 v60, v61, v60
	v_add_f32_e32 v60, v62, v60
	v_add_f32_e32 v60, v63, v60
	v_add_f32_e32 v60, v71, v60
	v_add_f32_e32 v60, v26, v60
	v_add_f32_e32 v60, v29, v60
	v_add_f32_e32 v60, v28, v60
	v_add_f32_e32 v60, v31, v60
	v_add_f32_e32 v60, v30, v60
	v_add_f32_e32 v60, v57, v60
	v_add_f32_e32 v60, v56, v60
	v_add_f32_e32 v59, v59, v60
	v_fma_f32 v58, v64, v58, -v21
	v_fma_f32 v59, v64, v59, -v18
	ds_write2st64_b32 v72, v58, v59 offset0:72 offset1:76
	v_add_f32_e32 v58, 0, v19
	v_add_f32_e32 v58, v18, v58
	v_cndmask_b32_e64 v59, v21, 0, s[0:1]
	v_add_f32_e32 v58, v59, v58
	v_add_f32_e32 v58, v65, v58
	v_cndmask_b32_e32 v60, 0, v23, vcc
	v_add_f32_e32 v58, v60, v58
	v_add_f32_e32 v58, v61, v58
	v_add_f32_e32 v58, v62, v58
	v_add_f32_e32 v58, v63, v58
	v_cndmask_b32_e64 v27, 0, v27, s[2:3]
	v_add_f32_e32 v58, v27, v58
	v_add_f32_e32 v58, v26, v58
	v_add_f32_e32 v58, v29, v58
	v_add_f32_e32 v58, v28, v58
	v_add_f32_e32 v58, v31, v58
	v_add_f32_e32 v58, v30, v58
	v_add_f32_e32 v58, v57, v58
	v_add_f32_e32 v56, v56, v58
	s_waitcnt lgkmcnt(14)
; DI void mixer_tile(unsigned char* smem_, const Params& p, int layer, const bf16_t* __restrict__ proj, bf16_t* __restrict__ y, int tile_) {
;     ...
;         float pv[47];
; #pragma unroll
;         for (int r = 0; r < 47; ++r) pv[r] = U[r * 256 + tid];
; #pragma unroll
;         for (int t = 0; t < 32; ++t) {
;             float s = 0.f;
; #pragma unroll
;             for (int j = 0; j < 16; ++j) s += (j < win) ? pv[t + 15 - j] : 0.f;
;             const int cnt = min(pos0 + t + 1, win);
;             U[t * 256 + tid] = s * __builtin_amdgcn_rcpf((float)cnt) - pv[t + 15];
;         }
	v_add_f32_e32 v58, 0, v14
	v_add_f32_e32 v58, v19, v58
	v_cndmask_b32_e64 v63, v18, 0, s[0:1]
	v_add_f32_e32 v58, v63, v58
	v_add_f32_e32 v58, v59, v58
	v_cndmask_b32_e32 v59, 0, v20, vcc
	v_add_f32_e32 v58, v59, v58
	v_add_f32_e32 v58, v60, v58
	v_add_f32_e32 v58, v61, v58
	v_add_f32_e32 v58, v62, v58
	v_cndmask_b32_e64 v24, 0, v24, s[2:3]
	v_add_f32_e32 v58, v24, v58
	v_add_f32_e32 v58, v27, v58
	v_add_f32_e32 v58, v26, v58
	v_add_f32_e32 v58, v29, v58
	v_add_f32_e32 v58, v28, v58
	v_add_f32_e32 v58, v31, v58
	v_add_f32_e32 v58, v30, v58
	v_add_f32_e32 v57, v57, v58
	v_fma_f32 v56, v64, v56, -v19
	v_fma_f32 v57, v64, v57, -v14
	ds_write2st64_b32 v72, v56, v57 offset0:80 offset1:84
	v_add_f32_e32 v56, 0, v15
	v_add_f32_e32 v56, v14, v56
	v_cndmask_b32_e64 v57, v19, 0, s[0:1]
	v_add_f32_e32 v56, v57, v56
	v_add_f32_e32 v56, v63, v56
	v_cndmask_b32_e32 v58, 0, v21, vcc
	v_add_f32_e32 v56, v58, v56
	v_add_f32_e32 v56, v59, v56
	v_add_f32_e32 v56, v60, v56
	v_add_f32_e32 v56, v61, v56
	v_cndmask_b32_e64 v25, 0, v25, s[2:3]
	v_add_f32_e32 v56, v25, v56
	v_add_f32_e32 v56, v24, v56
	v_add_f32_e32 v56, v27, v56
	v_add_f32_e32 v56, v26, v56
	v_add_f32_e32 v56, v29, v56
	v_add_f32_e32 v56, v28, v56
	v_add_f32_e32 v56, v31, v56
	v_add_f32_e32 v30, v30, v56
	v_add_f32_e32 v56, 0, v8
	v_add_f32_e32 v56, v15, v56
	v_cndmask_b32_e64 v61, v14, 0, s[0:1]
	v_add_f32_e32 v56, v61, v56
	v_add_f32_e32 v56, v57, v56
	v_cndmask_b32_e32 v57, 0, v18, vcc
	v_add_f32_e32 v56, v57, v56
	v_add_f32_e32 v56, v58, v56
	v_add_f32_e32 v56, v59, v56
	v_add_f32_e32 v56, v60, v56
	v_cndmask_b32_e64 v22, 0, v22, s[2:3]
	v_add_f32_e32 v56, v22, v56
	v_add_f32_e32 v56, v25, v56
	v_add_f32_e32 v56, v24, v56
	v_add_f32_e32 v56, v27, v56
	v_add_f32_e32 v56, v26, v56
	v_add_f32_e32 v56, v29, v56
	v_add_f32_e32 v56, v28, v56
	v_add_f32_e32 v31, v31, v56
	v_fma_f32 v30, v64, v30, -v15
	v_fma_f32 v31, v64, v31, -v8
	ds_write2st64_b32 v72, v30, v31 offset0:88 offset1:92
	v_add_f32_e32 v30, 0, v9
	v_add_f32_e32 v30, v8, v30
	v_cndmask_b32_e64 v31, v15, 0, s[0:1]
	v_add_f32_e32 v30, v31, v30
	v_add_f32_e32 v30, v61, v30
	v_cndmask_b32_e32 v56, 0, v19, vcc
	v_add_f32_e32 v30, v56, v30
	v_add_f32_e32 v30, v57, v30
	v_add_f32_e32 v30, v58, v30
	v_add_f32_e32 v30, v59, v30
	v_cndmask_b32_e64 v23, 0, v23, s[2:3]
	v_add_f32_e32 v30, v23, v30
	v_add_f32_e32 v30, v22, v30
	v_add_f32_e32 v30, v25, v30
	v_add_f32_e32 v30, v24, v30
	v_add_f32_e32 v30, v27, v30
	v_add_f32_e32 v30, v26, v30
	v_add_f32_e32 v30, v29, v30
	v_add_f32_e32 v28, v28, v30
	s_waitcnt lgkmcnt(14)
	v_add_f32_e32 v30, 0, v16
	v_add_f32_e32 v30, v9, v30
	v_cndmask_b32_e64 v59, v8, 0, s[0:1]
	v_add_f32_e32 v30, v59, v30
	v_add_f32_e32 v30, v31, v30
	v_cndmask_b32_e32 v31, 0, v14, vcc
	v_add_f32_e32 v30, v31, v30
	v_add_f32_e32 v30, v56, v30
	v_add_f32_e32 v30, v57, v30
	v_add_f32_e32 v30, v58, v30
	v_cndmask_b32_e64 v20, 0, v20, s[2:3]
	v_add_f32_e32 v30, v20, v30
	v_add_f32_e32 v30, v23, v30
	v_add_f32_e32 v30, v22, v30
	v_add_f32_e32 v30, v25, v30
	v_add_f32_e32 v30, v24, v30
	v_add_f32_e32 v30, v27, v30
	v_add_f32_e32 v30, v26, v30
	v_add_f32_e32 v29, v29, v30
	v_fma_f32 v28, v64, v28, -v9
	v_fma_f32 v29, v64, v29, -v16
	ds_write2st64_b32 v72, v28, v29 offset0:96 offset1:100
	v_add_f32_e32 v28, 0, v17
	v_add_f32_e32 v28, v16, v28
	v_cndmask_b32_e64 v29, v9, 0, s[0:1]
	v_add_f32_e32 v28, v29, v28
	v_add_f32_e32 v28, v59, v28
	v_cndmask_b32_e32 v30, 0, v15, vcc
	v_add_f32_e32 v28, v30, v28
	v_add_f32_e32 v28, v31, v28
	v_add_f32_e32 v28, v56, v28
	v_add_f32_e32 v28, v57, v28
	v_cndmask_b32_e64 v21, 0, v21, s[2:3]
	v_add_f32_e32 v28, v21, v28
	v_add_f32_e32 v28, v20, v28
	v_add_f32_e32 v28, v23, v28
	v_add_f32_e32 v28, v22, v28
	v_add_f32_e32 v28, v25, v28
	v_add_f32_e32 v28, v24, v28
	v_add_f32_e32 v28, v27, v28
	v_add_f32_e32 v26, v26, v28
	v_add_f32_e32 v28, 0, v10
	v_add_f32_e32 v28, v17, v28
	v_cndmask_b32_e64 v57, v16, 0, s[0:1]
	v_add_f32_e32 v28, v57, v28
	v_add_f32_e32 v28, v29, v28
	v_cndmask_b32_e32 v29, 0, v8, vcc
	v_add_f32_e32 v28, v29, v28
	v_add_f32_e32 v28, v30, v28
	v_add_f32_e32 v28, v31, v28
	v_add_f32_e32 v28, v56, v28
	v_cndmask_b32_e64 v18, 0, v18, s[2:3]
	v_add_f32_e32 v28, v18, v28
	v_add_f32_e32 v28, v21, v28
	v_add_f32_e32 v28, v20, v28
	v_add_f32_e32 v28, v23, v28
	v_add_f32_e32 v28, v22, v28
	v_add_f32_e32 v28, v25, v28
	v_add_f32_e32 v28, v24, v28
	v_add_f32_e32 v27, v27, v28
	v_fma_f32 v26, v64, v26, -v17
	v_fma_f32 v27, v64, v27, -v10
	ds_write2st64_b32 v72, v26, v27 offset0:104 offset1:108
	v_add_f32_e32 v26, 0, v11
	v_add_f32_e32 v26, v10, v26
	v_cndmask_b32_e64 v27, v17, 0, s[0:1]
	v_add_f32_e32 v26, v27, v26
	v_add_f32_e32 v26, v57, v26
	v_cndmask_b32_e32 v9, 0, v9, vcc
	v_add_f32_e32 v26, v9, v26
	v_add_f32_e32 v26, v29, v26
	v_add_f32_e32 v26, v30, v26
	v_add_f32_e32 v26, v31, v26
	v_cndmask_b32_e64 v19, 0, v19, s[2:3]
	v_add_f32_e32 v26, v19, v26
	v_add_f32_e32 v26, v18, v26
	v_add_f32_e32 v26, v21, v26
	v_add_f32_e32 v26, v20, v26
	v_add_f32_e32 v26, v23, v26
	v_add_f32_e32 v26, v22, v26
	v_add_f32_e32 v26, v25, v26
	v_add_f32_e32 v24, v24, v26
	s_waitcnt lgkmcnt(14)
; #define MFMA32(a, b, c) __builtin_amdgcn_mfma_f32_32x32x16_bf16((a), (b), (c), 0, 0, 0)
; DI unsigned pk2(float lo, float hi) { const f32x2 v = {lo, hi}; return __builtin_bit_cast(unsigned, __builtin_convertvector(v, bf16x2_t)); }
; DI void mixer_tile(unsigned char* smem_, const Params& p, int layer, const bf16_t* __restrict__ proj, bf16_t* __restrict__ y, int tile_) {
;     ...
;             U[t * 256 + tid] = s * __builtin_amdgcn_rcpf((float)cnt) - pv[t + 15];
;         }
;         __syncthreads();
;         f32x16 acc[2];
; #pragma unroll
;         for (int i = 0; i < 16; ++i) { acc[0][i] = 0.f; acc[1][i] = 0.f; }
; #pragma unroll
;         for (int kk = 0; kk < 4; ++kk) {
;             const float* pp = U + l31 * 256 + g * 64 + 16 * kk + 8 * hi;
;             const f32x4 pa = *(const f32x4*)(pp), pb = *(const f32x4*)(pp + 4);
;             u32x4 pk; pk.x = pk2(pa.x, pa.y); pk.y = pk2(pa.z, pa.w); pk.z = pk2(pb.x, pb.y); pk.w = pk2(pb.z, pb.w);
;             const bf16x8 pf = __builtin_bit_cast(bf16x8, pk);
;             acc[0] = MFMA32(wf[0][kk], pf, acc[0]);
;             acc[1] = MFMA32(wf[1][kk], pf, acc[1]);
;         }
;         const float* scp = p.in[7] + layer * 256 + g * 64;
;         bf16_t* yr = y + (size_t)(tok0 + l31) * PA + 256 + g * 64 + 4 * hi;
; #pragma unroll
;         for (int eh = 0; eh < 2; ++eh)
; #pragma unroll
;             for (int gq = 0; gq < 4; ++gq) {
;                 const f32x4 sc = *(const f32x4*)(scp + 32 * eh + 8 * gq + 4 * hi);
;                 u32x2 wv; wv.x = pk2(acc[eh][4 * gq] * sc.x, acc[eh][4 * gq + 1] * sc.y); wv.y = pk2(acc[eh][4 * gq + 2] * sc.z, acc[eh][4 * gq + 3] * sc.w);
;                 *(u32x2*)(yr + 32 * eh + 8 * gq) = wv;
;             }
	v_add_f32_e32 v26, 0, v12
	v_add_f32_e32 v26, v11, v26
	v_cndmask_b32_e64 v28, v10, 0, s[0:1]
	v_add_f32_e32 v26, v28, v26
	v_add_f32_e32 v26, v27, v26
	v_cndmask_b32_e32 v16, 0, v16, vcc
	v_add_f32_e32 v26, v16, v26
	v_add_f32_e32 v26, v9, v26
	v_add_f32_e32 v26, v29, v26
	v_add_f32_e32 v26, v30, v26
	v_cndmask_b32_e64 v14, 0, v14, s[2:3]
	v_add_f32_e32 v26, v14, v26
	v_add_f32_e32 v26, v19, v26
	v_add_f32_e32 v26, v18, v26
	v_add_f32_e32 v26, v21, v26
	v_add_f32_e32 v26, v20, v26
	v_add_f32_e32 v26, v23, v26
	v_add_f32_e32 v26, v22, v26
	v_add_f32_e32 v25, v25, v26
	v_fma_f32 v24, v64, v24, -v11
	v_fma_f32 v25, v64, v25, -v12
	ds_write2st64_b32 v72, v24, v25 offset0:112 offset1:116
	v_add_f32_e32 v24, 0, v13
	v_add_f32_e32 v24, v12, v24
	v_cndmask_b32_e64 v11, v11, 0, s[0:1]
	v_add_f32_e32 v24, v11, v24
	v_add_f32_e32 v24, v28, v24
	v_cndmask_b32_e32 v17, 0, v17, vcc
	v_add_f32_e32 v24, v17, v24
	v_add_f32_e32 v24, v16, v24
	v_add_f32_e32 v24, v9, v24
	v_add_f32_e32 v24, v29, v24
	v_cndmask_b32_e64 v15, 0, v15, s[2:3]
	v_add_f32_e32 v24, v15, v24
	v_add_f32_e32 v24, v14, v24
	v_add_f32_e32 v24, v19, v24
	v_add_f32_e32 v24, v18, v24
	v_add_f32_e32 v24, v21, v24
	v_add_f32_e32 v24, v20, v24
	v_add_f32_e32 v24, v23, v24
	v_add_f32_e32 v22, v22, v24
	v_add_f32_e32 v24, 0, v70
	v_fma_f32 v22, v64, v22, -v13
	v_add_f32_e32 v13, v13, v24
	v_cndmask_b32_e64 v12, v12, 0, s[0:1]
	v_add_f32_e32 v12, v12, v13
	v_add_f32_e32 v11, v11, v12
	v_cndmask_b32_e32 v10, 0, v10, vcc
	v_add_f32_e32 v10, v10, v11
	v_add_f32_e32 v10, v17, v10
	v_add_f32_e32 v10, v16, v10
	v_add_f32_e32 v9, v9, v10
	v_cndmask_b32_e64 v8, 0, v8, s[2:3]
	v_add_f32_e32 v8, v8, v9
	v_add_f32_e32 v8, v15, v8
	v_add_f32_e32 v8, v14, v8
	v_add_f32_e32 v8, v19, v8
	v_add_f32_e32 v8, v18, v8
	v_add_f32_e32 v8, v21, v8
	v_add_f32_e32 v8, v20, v8
	v_add_f32_e32 v8, v23, v8
	v_fma_f32 v8, v64, v8, -v70
	v_and_b32_e32 v70, 0xc0, v68
	ds_write2st64_b32 v72, v22, v8 offset0:120 offset1:124
	v_lshl_add_u32 v8, v67, 10, s19
	v_lshlrev_b32_e32 v64, 2, v70
	v_and_b32_e32 v9, 32, v68
	v_add3_u32 v65, v8, v64, v9
	s_waitcnt lgkmcnt(0)
	s_barrier
	ds_read_b128 v[8:11], v65
	ds_read_b128 v[12:15], v65 offset:16
	ds_read_b128 v[56:59], v65 offset:64
	ds_read_b128 v[60:63], v65 offset:80
	s_not_b32 s2, s18
	v_mov_b32_e32 v68, 0
	s_waitcnt lgkmcnt(3)
	v_cvt_pk_bf16_f32 v8, v8, v9
	v_cvt_pk_bf16_f32 v9, v10, v11
	s_waitcnt lgkmcnt(2)
	v_cvt_pk_bf16_f32 v10, v12, v13
	v_cvt_pk_bf16_f32 v11, v14, v15
	s_waitcnt lgkmcnt(1)
	v_cvt_pk_bf16_f32 v56, v56, v57
	v_cvt_pk_bf16_f32 v57, v58, v59
	v_mfma_f32_32x32x16_bf16 v[16:31], v[0:3], v[8:11], 0
	s_waitcnt lgkmcnt(0)
	v_cvt_pk_bf16_f32 v58, v60, v61
	v_cvt_pk_bf16_f32 v59, v62, v63
	v_mov_b32_e32 v60, 0
	v_mov_b32_e32 v71, 0
	v_mfma_f32_32x32x16_bf16 v[0:15], v[4:7], v[8:11], 0
	v_mfma_f32_32x32x16_bf16 v[16:31], v[32:35], v[56:59], v[16:31]
	v_mfma_f32_32x32x16_bf16 v[0:15], v[44:47], v[56:59], v[0:15]
	ds_read_b128 v[32:35], v65 offset:128
	ds_read_b128 v[44:47], v65 offset:144
	s_waitcnt lgkmcnt(1)
	v_cvt_pk_bf16_f32 v32, v32, v33
	v_cvt_pk_bf16_f32 v33, v34, v35
	s_waitcnt lgkmcnt(0)
	v_cvt_pk_bf16_f32 v34, v44, v45
	v_cvt_pk_bf16_f32 v35, v46, v47
	s_nop 1
	v_mfma_f32_32x32x16_bf16 v[16:31], v[36:39], v[32:35], v[16:31]
	v_mfma_f32_32x32x16_bf16 v[0:15], v[48:51], v[32:35], v[0:15]
	ds_read_b128 v[32:35], v65 offset:192
	ds_read_b128 v[36:39], v65 offset:208
	v_mov_b32_e32 v65, v129
	s_waitcnt lgkmcnt(1)
	v_cvt_pk_bf16_f32 v32, v32, v33
	v_cvt_pk_bf16_f32 v33, v34, v35
	s_waitcnt lgkmcnt(0)
	v_cvt_pk_bf16_f32 v34, v36, v37
	v_cvt_pk_bf16_f32 v35, v38, v39
	v_lshlrev_b32_e32 v36, 1, v70
	v_mov_b32_e32 v37, v129
	v_mfma_f32_32x32x16_bf16 v[16:31], v[40:43], v[32:35], v[16:31]
	v_mov_b32_e32 v70, 0
	v_mfma_f32_32x32x16_bf16 v[0:15], v[52:55], v[32:35], v[0:15]
	v_or_b32_e32 v32, s17, v67
	v_ashrrev_i32_e32 v33, 31, v32
	v_lshlrev_b64 v[32:33], 11, v[32:33]
	v_lshl_add_u64 v[32:33], s[88:89], 0, v[32:33]
	v_lshl_add_u64 v[32:33], v[32:33], 0, v[36:37]
	v_lshlrev_b32_e32 v36, 3, v69
	v_lshl_add_u64 v[34:35], s[12:13], 0, v[64:65]
	v_lshl_add_u64 v[32:33], v[32:33], 0, v[36:37]
	v_lshlrev_b32_e32 v36, 4, v69
	v_lshl_add_u64 v[34:35], v[34:35], 0, v[36:37]
	global_load_dwordx4 v[36:39], v[34:35], off
	global_load_dwordx4 v[40:43], v[34:35], off offset:32
	global_load_dwordx4 v[44:47], v[34:35], off offset:64
	global_load_dwordx4 v[48:51], v[34:35], off offset:96
	global_load_dwordx4 v[52:55], v[34:35], off offset:128
	v_mov_b32_e32 v64, 0
	v_mov_b32_e32 v65, 0
	v_mov_b32_e32 v67, 0
	v_mov_b32_e32 v69, 0
	s_waitcnt vmcnt(0)
	v_pk_mul_f32 v[36:37], v[16:17], v[36:37]
	v_pk_mul_f32 v[38:39], v[18:19], v[38:39]
	v_cvt_pk_bf16_f32 v36, v36, v37
	v_cvt_pk_bf16_f32 v37, v38, v39
	global_store_dwordx2 v[32:33], v[36:37], off offset:512
	global_load_dwordx4 v[36:39], v[34:35], off offset:160
	v_pk_mul_f32 v[40:41], v[20:21], v[40:41]
	v_pk_mul_f32 v[42:43], v[22:23], v[42:43]
	v_cvt_pk_bf16_f32 v40, v40, v41
	v_cvt_pk_bf16_f32 v41, v42, v43
	global_store_dwordx2 v[32:33], v[40:41], off offset:528
	global_load_dwordx4 v[40:43], v[34:35], off offset:192
	v_pk_mul_f32 v[44:45], v[24:25], v[44:45]
	v_pk_mul_f32 v[46:47], v[26:27], v[46:47]
	v_cvt_pk_bf16_f32 v44, v44, v45
	v_cvt_pk_bf16_f32 v45, v46, v47
	global_store_dwordx2 v[32:33], v[44:45], off offset:544
	global_load_dwordx4 v[44:47], v[34:35], off offset:224
	v_pk_mul_f32 v[48:49], v[28:29], v[48:49]
	v_pk_mul_f32 v[50:51], v[30:31], v[50:51]
	v_cvt_pk_bf16_f32 v48, v48, v49
	v_cvt_pk_bf16_f32 v49, v50, v51
	global_store_dwordx2 v[32:33], v[48:49], off offset:560
	v_pk_mul_f32 v[52:53], v[0:1], v[52:53]
	v_pk_mul_f32 v[54:55], v[2:3], v[54:55]
	v_cvt_pk_bf16_f32 v52, v52, v53
	v_cvt_pk_bf16_f32 v53, v54, v55
	global_store_dwordx2 v[32:33], v[52:53], off offset:576
	s_waitcnt vmcnt(0)
	v_pk_mul_f32 v[36:37], v[4:5], v[36:37]
	v_pk_mul_f32 v[38:39], v[6:7], v[38:39]
	v_cvt_pk_bf16_f32 v36, v36, v37
	v_cvt_pk_bf16_f32 v37, v38, v39
	global_store_dwordx2 v[32:33], v[36:37], off offset:592
	v_pk_mul_f32 v[40:41], v[8:9], v[40:41]
	v_pk_mul_f32 v[42:43], v[10:11], v[42:43]
	v_cvt_pk_bf16_f32 v40, v40, v41
	v_cvt_pk_bf16_f32 v41, v42, v43
	global_store_dwordx2 v[32:33], v[40:41], off offset:608
	v_pk_mul_f32 v[44:45], v[12:13], v[44:45]
	v_pk_mul_f32 v[46:47], v[14:15], v[46:47]
	v_cvt_pk_bf16_f32 v44, v44, v45
	v_cvt_pk_bf16_f32 v45, v46, v47
	global_store_dwordx2 v[32:33], v[44:45], off offset:624
	v_lshlrev_b32_e32 v0, 2, v66
	v_add_u32_e32 v1, -2, v0
	v_cmp_lt_i32_e32 vcc, s2, v1
	v_add_u32_e32 v96, s17, v1
	v_mov_b32_e32 v66, 0
	s_barrier
	s_and_saveexec_b64 s[0:1], vcc
	s_cbranch_execz .LBB0_180
	v_mad_i64_i32 v[2:3], s[18:19], v96, s70, v[88:89]
	global_load_dwordx4 v[64:67], v[2:3], off offset:1536
	global_load_dwordx4 v[68:71], v[2:3], off offset:2560

; DI void attn_unit(unsigned char* smem, const bf16_t* __restrict__ proj, bf16_t* __restrict__ y, int bh, int qb) {
;     ...
;         {
;             int f = 1;
; #pragma unroll
;             for (int w_ = 0; w_ < 8; ++w_) f &= flags[(kt & 1) * 8 + w_];
;             if (f) break;
;         }
;     ...
;         buf ^= 1;
.LBB0_205:
	s_or_b64 exec, exec, s[0:1]
	s_lshl_b32 s0, s50, 2
	s_add_i32 s50, s0, 0
	s_add_i32 s51, s50, 0x8c00
	s_mov_b64 s[0:1], src_shared_base
	v_mov_b32_e32 v32, s51
	v_mov_b32_e32 v33, s1
	s_add_i32 s0, s50, 0x8c04
	s_waitcnt lgkmcnt(0)
	s_barrier
	v_and_b32_e32 v34, 7, v192
	v_lshl_add_u32 v34, v34, 2, s51
	ds_read_b32 v34, v34
	s_mov_b64 s[0:1], -1
	s_waitcnt lgkmcnt(0)
	v_and_b32_e32 v34, 1, v34
	v_cmp_eq_u32_e32 vcc, 0, v34
	s_cmp_lg_u64 vcc, 0
	s_cselect_b64 vcc, exec, 0
	s_and_saveexec_b64 s[50:51], vcc
	s_cbranch_execz .LBB0_194
	s_xor_b32 s57, s57, 1
	s_add_i32 s60, s60, -1
	s_add_i32 s58, s58, -8
	s_sub_i32 s59, s59, 64
	s_sub_i32 s73, s73, 64
	s_cmp_eq_u32 s60, -2
	s_cselect_b64 s[0:1], -1, 0
	s_orn2_b64 s[0:1], s[0:1], exec
	s_branch .LBB0_194
